# relax_epires2 + P4 EpiRes2 residual-base loads pipelined two half-steps ahead (register shift by 8, waits regenerated from dependencies)
# baseline (speedup 1.0000x reference)
;     __device__ __forceinline__ void operator()(const f32x4 (&acc)[2][2][4][2], const Unit& u, int wr, int wc, int fr, int fq) const {
;     ...
;         const int urow = u.pm * BM + wr * 64, ucol = u.pn * BM + wc * 32;
;         const size_t ubase = (size_t)urow * ldc + ucol;
;         const char* bp = (const char*)(base + ubase); char* op = (char*)(out + ubase); char* zp = (char*)(zb + ubase);
;         const char* sp = (const char*)(bstats + 2 * (size_t)urow); float* osp = ostats + 2 * (size_t)urow;
;         const unsigned l4 = (unsigned)(fr * ldc + 8 * fq) * 4u, l2 = (unsigned)(fr * ldc + 8 * fq) * 2u, ls = (unsigned)fr * 8u;
;         const int col0 = ucol + 8 * fq;
;         f32x4 gv[2][2], cv[2][2];
; #pragma unroll
;         for (int bj = 0; bj < 2; ++bj)
; #pragma unroll
;             for (int n = 0; n < 2; ++n) { gv[bj][n] = *(const f32x4*)(bg + col0 + bj * HALF + 4 * n) * alpha;
;                 cv[bj][n] = *(const f32x4*)(bb + col0 + bj * HALF + 4 * n) * alpha + *(const f32x4*)(bias + col0 + bj * HALF + 4 * n); }
;         f32x2 sv_c = *(const f32x2*)(sp + ls);
;         f32x4 p0 = *(const f32x4*)(bp + l4), p1 = *(const f32x4*)(bp + l4 + 16);
; #pragma unroll
;         for (int g = 0; g < 8; ++g) { const int ai = g >> 2, m = g & 3; const int rr = ai * HALF + m * 16, rn = ((g + 1) >> 2) * HALF + ((g + 1) & 3) * 16;
;             f32x2 sv_n = sv_c; if (g + 1 < 8) sv_n = *(const f32x2*)(sp + (size_t)rn * 8 + ls);
;             float mu, r; stats_mr(sv_c, mu, r); float s1 = 0.f, s2 = 0.f;
; #pragma unroll
;             for (int bj = 0; bj < 2; ++bj) { const size_t ro = (size_t)rr * ldc + bj * HALF;
;                 f32x4 q0 = p0, q1 = p1;
;                 if (bj == 0) { q0 = *(const f32x4*)(bp + (ro + HALF) * 4 + l4); q1 = *(const f32x4*)(bp + (ro + HALF) * 4 + l4 + 16); }
;                 else if (g + 1 < 8) { q0 = *(const f32x4*)(bp + (size_t)rn * ldc * 4 + l4); q1 = *(const f32x4*)(bp + (size_t)rn * ldc * 4 + l4 + 16); }
;                 const f32x4 z0 = gv[bj][0] * ((p0 - mu) * r) + acc[ai][bj][m][0] + cv[bj][0], z1 = gv[bj][1] * ((p1 - mu) * r) + acc[ai][bj][m][1] + cv[bj][1];
;                 *(f32x4*)(op + ro * 4 + l4) = z0; *(f32x4*)(op + ro * 4 + l4 + 16) = z1;
;                 s1 += ((z0[0] + z0[1]) + (z0[2] + z0[3])) + ((z1[0] + z1[1]) + (z1[2] + z1[3]));
.LBB0_730:
	s_lshl_b32 s1, s83, 8
	s_add_i32 s24, s1, s93
	s_lshl_b32 s1, s82, 8
	s_or_b32 s1, s1, s94
	v_or_b32_e32 v130, s1, v1
	v_ashrrev_i32_e32 v131, 31, v130
	v_lshlrev_b64 v[130:131], 2, v[130:131]
	v_lshl_add_u64 v[160:161], s[48:49], 0, v[130:131]
	v_lshl_add_u64 v[168:169], s[50:51], 0, v[130:131]
	v_lshl_add_u64 v[202:203], s[44:45], 0, v[130:131]
	global_load_dwordx4 v[130:133], v[160:161], off offset:16
	global_load_dwordx4 v[134:137], v[160:161], off
	s_ashr_i32 s25, s24, 31
	s_ashr_i32 s4, s1, 31
	s_lshl_b64 s[34:35], s[24:25], 10
	s_add_u32 s34, s34, s1
	s_addc_u32 s35, s35, s4
	s_lshl_b64 s[60:61], s[34:35], 2
	s_add_u32 s70, s96, s60
	s_addc_u32 s71, s95, s61
	s_lshl_b64 s[24:25], s[24:25], 3
	v_lshl_add_u64 v[204:205], v[148:149], 0, s[24:25]
	s_mov_b64 s[4:5], 0x10000
	s_add_u32 s82, s46, s24
	s_addc_u32 s83, s47, s25
	s_waitcnt vmcnt(1)
	v_pk_mul_f32 v[194:195], v[132:133], s[26:27] op_sel_hi:[1,0]
	s_waitcnt vmcnt(0)
	v_pk_mul_f32 v[162:163], v[136:137], s[26:27] op_sel_hi:[1,0]
	v_pk_mul_f32 v[170:171], v[134:135], s[26:27] op_sel_hi:[1,0]
	global_load_dwordx4 v[134:137], v[168:169], off offset:16
	global_load_dwordx4 v[164:167], v[168:169], off
	global_load_dwordx4 v[172:175], v[202:203], off offset:16
	global_load_dwordx4 v[176:179], v[202:203], off
	v_pk_mul_f32 v[196:197], v[130:131], s[26:27] op_sel_hi:[1,0]
	s_waitcnt vmcnt(1)
	v_pk_fma_f32 v[190:191], v[136:137], s[26:27], v[174:175] op_sel_hi:[1,0,1]
	v_pk_fma_f32 v[192:193], v[134:135], s[26:27], v[172:173] op_sel_hi:[1,0,1]
	global_load_dwordx4 v[130:133], v[160:161], off offset:528
	global_load_dwordx4 v[134:137], v[160:161], off offset:512
	s_waitcnt vmcnt(2)
	v_pk_fma_f32 v[186:187], v[166:167], s[26:27], v[178:179] op_sel_hi:[1,0,1]
	v_pk_fma_f32 v[188:189], v[164:165], s[26:27], v[176:177] op_sel_hi:[1,0,1]
	s_waitcnt vmcnt(1)
	v_pk_mul_f32 v[178:179], v[130:131], s[26:27] op_sel_hi:[1,0]
	s_waitcnt vmcnt(0)
	v_pk_mul_f32 v[160:161], v[136:137], s[26:27] op_sel_hi:[1,0]
	v_pk_mul_f32 v[164:165], v[134:135], s[26:27] op_sel_hi:[1,0]
	global_load_dwordx4 v[134:137], v[168:169], off offset:528
	s_nop 0
	global_load_dwordx4 v[166:169], v[168:169], off offset:512
	s_nop 0
	global_load_dwordx4 v[198:201], v[202:203], off offset:528
	global_load_dwordx4 v[172:175], v[202:203], off offset:512
	global_load_dwordx2 v[130:131], v[204:205], off
	v_lshl_add_u64 v[202:203], s[70:71], 0, v[150:151]
	global_load_dwordx4 v[212:215], v[202:203], off offset:16
	global_load_dwordx4 v[216:219], v[202:203], off
	global_load_dwordx2 v[206:207], v[204:205], off offset:128
	s_waitcnt vmcnt(4)
	v_pk_fma_f32 v[174:175], v[168:169], s[26:27], v[174:175] op_sel_hi:[1,0,1]
	s_waitcnt vmcnt(3)
	v_pk_mul_f32 v[210:211], v[130:131], s[54:55] op_sel_hi:[1,0]
	v_pk_fma_f32 v[176:177], v[166:167], s[26:27], v[172:173] op_sel_hi:[1,0,1]
	v_fma_f32 v130, -v210, v210, v211
	v_add_f32_e32 v130, 0x3727c5ac, v130
	v_pk_mul_f32 v[172:173], v[132:133], s[26:27] op_sel_hi:[1,0]
	v_pk_fma_f32 v[166:167], v[136:137], s[26:27], v[200:201] op_sel_hi:[1,0,1]
	v_pk_fma_f32 v[168:169], v[134:135], s[26:27], v[198:199] op_sel_hi:[1,0,1]
	v_rsq_f32_e32 v208, v130
	global_load_dwordx4 v[130:133], v[202:203], off offset:528
	global_load_dwordx4 v[134:137], v[202:203], off offset:512
	v_add_co_u32_e32 v234, vcc, 0x10000, v202
	v_addc_co_u32_e32 v235, vcc, 0, v203, vcc
	global_load_dwordx4 v[238:241], v[234:235], off
	s_nop 0
	global_load_dwordx4 v[234:237], v[234:235], off offset:16
	s_waitcnt vmcnt(5)
	v_sub_f32_e32 v217, v217, v210
	v_sub_f32_e32 v216, v216, v210
	v_sub_f32_e32 v219, v219, v210
	v_sub_f32_e32 v218, v218, v210
	v_pk_mul_f32 v[218:219], v[218:219], v[208:209] op_sel_hi:[1,0]
	v_pk_mul_f32 v[216:217], v[216:217], v[208:209] op_sel_hi:[1,0]
	v_sub_f32_e32 v213, v213, v210
	v_sub_f32_e32 v212, v212, v210
	v_sub_f32_e32 v215, v215, v210
	v_sub_f32_e32 v214, v214, v210
	v_pk_fma_f32 v[126:127], v[170:171], v[216:217], v[126:127]
	v_pk_fma_f32 v[128:129], v[162:163], v[218:219], v[128:129]
	v_pk_mul_f32 v[214:215], v[214:215], v[208:209] op_sel_hi:[1,0]
	v_pk_mul_f32 v[212:213], v[212:213], v[208:209] op_sel_hi:[1,0]
	v_pk_add_f32 v[128:129], v[186:187], v[128:129]
	v_pk_add_f32 v[126:127], v[188:189], v[126:127]
	v_pk_fma_f32 v[122:123], v[196:197], v[212:213], v[122:123]
	v_pk_fma_f32 v[124:125], v[194:195], v[214:215], v[124:125]
	v_pk_add_f32 v[122:123], v[192:193], v[122:123]
	v_pk_add_f32 v[124:125], v[190:191], v[124:125]
	v_add_f32_e32 v211, v126, v127
	v_add_f32_e32 v212, v128, v129
	v_add_f32_e32 v211, v211, v212
	v_add_f32_e32 v212, v122, v123
	v_add_f32_e32 v213, v124, v125
	v_add_f32_e32 v212, v212, v213
	v_add_f32_e32 v211, v211, v212
	v_add_f32_e32 v214, 0, v211
	v_mul_f32_e32 v211, v127, v127
	v_mul_f32_e32 v212, v129, v129
	v_fmac_f32_e32 v211, v126, v126
	v_fmac_f32_e32 v212, v128, v128
	v_add_f32_e32 v211, v211, v212
	v_mul_f32_e32 v212, v123, v123
	v_mul_f32_e32 v213, v125, v125
	v_lshl_add_u64 v[200:201], v[152:153], 0, s[60:61]
	v_fmac_f32_e32 v212, v122, v122
	v_fmac_f32_e32 v213, v124, v124
	global_store_dwordx4 v[200:201], v[126:129], off nt
	global_store_dwordx4 v[200:201], v[122:125], off offset:16 nt
	v_add_f32_e32 v212, v212, v213
	v_cvt_pk_bf16_f32 v126, v126, v127
	v_cvt_pk_bf16_f32 v127, v128, v129
	v_cvt_pk_bf16_f32 v128, v122, v123
	v_lshl_add_u64 v[198:199], s[34:35], 1, v[154:155]
	v_lshl_add_u64 v[122:123], v[202:203], 0, s[4:5]
	s_mov_b32 s4, 0x10000
	v_add_f32_e32 v211, v211, v212
	v_add_co_u32_e32 v212, vcc, s4, v202
	v_cvt_pk_bf16_f32 v129, v124, v125
	global_store_dwordx4 v[198:199], v[126:129], off
	s_nop 0
	v_addc_co_u32_e32 v213, vcc, 0, v203, vcc
	s_nop 0
	v_add_co_u32_e32 v122, vcc, 0x10200, v202
	v_addc_co_u32_e32 v123, vcc, 0, v203, vcc
	global_load_dwordx4 v[126:129], v[122:123], off
	s_nop 0
	global_load_dwordx4 v[122:125], v[122:123], off offset:16
	s_waitcnt vmcnt(8)
; __device__ __forceinline__ unsigned cvt_pk_bf16(float lo, float hi) { unsigned r; asm volatile("v_cvt_pk_bf16_f32 %0, %1, %2" : "=v"(r) : "v"(lo), "v"(hi)); return r; }
; __device__ __forceinline__ void stats_mr(const f32x2 s, float& mu, float& r) { mu = s.x * (1.0f / 1024.0f); const float var = s.y * (1.0f / 1024.0f) - mu * mu; r = __builtin_amdgcn_rsqf(var + 1e-5f); }
;     __device__ __forceinline__ void operator()(const f32x4 (&acc)[2][2][4][2], const Unit& u, int wr, int wc, int fr, int fq) const {
;     ...
;         for (int g = 0; g < 8; ++g) { const int ai = g >> 2, m = g & 3; const int rr = ai * HALF + m * 16, rn = ((g + 1) >> 2) * HALF + ((g + 1) & 3) * 16;
;             f32x2 sv_n = sv_c; if (g + 1 < 8) sv_n = *(const f32x2*)(sp + (size_t)rn * 8 + ls);
;             float mu, r; stats_mr(sv_c, mu, r); float s1 = 0.f, s2 = 0.f;
; #pragma unroll
;             for (int bj = 0; bj < 2; ++bj) { const size_t ro = (size_t)rr * ldc + bj * HALF;
;                 f32x4 q0 = p0, q1 = p1;
;                 if (bj == 0) { q0 = *(const f32x4*)(bp + (ro + HALF) * 4 + l4); q1 = *(const f32x4*)(bp + (ro + HALF) * 4 + l4 + 16); }
;                 else if (g + 1 < 8) { q0 = *(const f32x4*)(bp + (size_t)rn * ldc * 4 + l4); q1 = *(const f32x4*)(bp + (size_t)rn * ldc * 4 + l4 + 16); }
;                 const f32x4 z0 = gv[bj][0] * ((p0 - mu) * r) + acc[ai][bj][m][0] + cv[bj][0], z1 = gv[bj][1] * ((p1 - mu) * r) + acc[ai][bj][m][1] + cv[bj][1];
;                 *(f32x4*)(op + ro * 4 + l4) = z0; *(f32x4*)(op + ro * 4 + l4 + 16) = z1;
;                 s1 += ((z0[0] + z0[1]) + (z0[2] + z0[3])) + ((z1[0] + z1[1]) + (z1[2] + z1[3]));
;                 s2 += ((z0[0] * z0[0] + z0[1] * z0[1]) + (z0[2] * z0[2] + z0[3] * z0[3])) + ((z1[0] * z1[0] + z1[1] * z1[1]) + (z1[2] * z1[2] + z1[3] * z1[3]));
;                 if (zb) { u32x4 w; w.x = cvt_pk_bf16(z0[0], z0[1]); w.y = cvt_pk_bf16(z0[2], z0[3]); w.z = cvt_pk_bf16(z1[0], z1[1]); w.w = cvt_pk_bf16(z1[2], z1[3]); *(u32x4*)(zp + ro * 2 + l2) = w; }
;                 p0 = q0; p1 = q1; }
;             s1 += __shfl_xor(s1, 16); s2 += __shfl_xor(s2, 16); s1 += __shfl_xor(s1, 32); s2 += __shfl_xor(s2, 32);
;             if (fq == 0) { atomicAdd(osp + 2 * (rr + fr), s1); atomicAdd(osp + 2 * (rr + fr) + 1, s2); }
;             sv_c = sv_n; }
	v_sub_f32_e32 v131, v131, v210
	s_waitcnt vmcnt(7)
	v_sub_f32_e32 v135, v135, v210
	v_sub_f32_e32 v134, v134, v210
	v_sub_f32_e32 v137, v137, v210
	v_sub_f32_e32 v136, v136, v210
	v_pk_mul_f32 v[136:137], v[136:137], v[208:209] op_sel_hi:[1,0]
	v_pk_mul_f32 v[134:135], v[134:135], v[208:209] op_sel_hi:[1,0]
	v_sub_f32_e32 v130, v130, v210
	v_sub_f32_e32 v133, v133, v210
	v_sub_f32_e32 v132, v132, v210
	v_pk_fma_f32 v[118:119], v[164:165], v[134:135], v[118:119]
	v_pk_fma_f32 v[120:121], v[160:161], v[136:137], v[120:121]
	v_pk_mul_f32 v[132:133], v[132:133], v[208:209] op_sel_hi:[1,0]
	v_pk_mul_f32 v[130:131], v[130:131], v[208:209] op_sel_hi:[1,0]
	v_pk_add_f32 v[120:121], v[174:175], v[120:121]
	v_pk_add_f32 v[118:119], v[176:177], v[118:119]
	v_pk_fma_f32 v[114:115], v[178:179], v[130:131], v[114:115]
	v_pk_fma_f32 v[116:117], v[172:173], v[132:133], v[116:117]
	v_pk_add_f32 v[114:115], v[168:169], v[114:115]
	v_pk_add_f32 v[116:117], v[166:167], v[116:117]
	v_add_f32_e32 v130, v118, v119
	v_add_f32_e32 v131, v120, v121
	v_add_f32_e32 v130, v130, v131
	v_add_f32_e32 v131, v114, v115
	v_add_f32_e32 v132, v116, v117
	v_add_f32_e32 v131, v131, v132
	v_add_f32_e32 v130, v130, v131
	v_mul_f32_e32 v131, v119, v119
	v_mul_f32_e32 v132, v121, v121
	v_fmac_f32_e32 v131, v118, v118
	v_fmac_f32_e32 v132, v120, v120
	global_store_dwordx4 v[200:201], v[118:121], off offset:512 nt
	global_store_dwordx4 v[200:201], v[114:117], off offset:528 nt
	v_add_f32_e32 v131, v131, v132
	v_mul_f32_e32 v132, v115, v115
	v_mul_f32_e32 v133, v117, v117
	v_cvt_pk_bf16_f32 v118, v118, v119
	v_cvt_pk_bf16_f32 v119, v120, v121
	v_cvt_pk_bf16_f32 v120, v114, v115
	v_and_b32_e32 v115, 64, v224
	v_fmac_f32_e32 v132, v114, v114
	v_fmac_f32_e32 v133, v116, v116
	v_cvt_pk_bf16_f32 v121, v116, v117
	v_xor_b32_e32 v114, 16, v224
	v_add_u32_e32 v116, 64, v115
	v_add_f32_e32 v132, v132, v133
	v_cmp_lt_i32_e32 vcc, v114, v116
	v_add_f32_e32 v131, v131, v132
	v_add_f32_e32 v130, v130, v214
	v_cndmask_b32_e32 v114, v224, v114, vcc
	v_add_f32_e32 v131, v211, v131
	v_lshlrev_b32_e32 v133, 2, v114
	ds_bpermute_b32 v114, v133, v130
	ds_bpermute_b32 v115, v133, v131
	v_xor_b32_e32 v117, 32, v224
	v_cmp_lt_i32_e32 vcc, v117, v116
	v_lshlrev_b32_e32 v137, 2, v146
	s_waitcnt lgkmcnt(1)
	v_add_f32_e32 v114, v130, v114
	v_cndmask_b32_e32 v116, v224, v117, vcc
	s_waitcnt lgkmcnt(0)
	v_add_f32_e32 v115, v131, v115
	v_lshlrev_b32_e32 v136, 2, v116
	ds_bpermute_b32 v116, v136, v114
	ds_bpermute_b32 v117, v136, v115
	global_store_dwordx4 v[198:199], v[118:121], off offset:256
	s_and_saveexec_b64 s[24:25], s[40:41]
	s_mov_b32 s5, 0x90000
	s_cbranch_execz .LBB0_732
	s_waitcnt lgkmcnt(1)
	v_add_f32_e32 v114, v114, v116
	s_waitcnt lgkmcnt(0)
	v_add_f32_e32 v115, v115, v117
	global_atomic_add_f32 v137, v114, s[82:83]
	global_atomic_add_f32 v137, v115, s[82:83] offset:4
.LBB0_732:
	s_or_b64 exec, exec, s[24:25]
	v_pk_mul_f32 v[134:135], v[206:207], s[54:55] op_sel_hi:[1,0]
	s_mov_b64 s[24:25], 0x10200
	v_fma_f32 v114, -v134, v134, v135
	v_add_f32_e32 v114, 0x3727c5ac, v114
	v_rsq_f32_e32 v132, v114
	v_lshl_add_u64 v[114:115], v[202:203], 0, s[24:25]
	global_load_dwordx2 v[130:131], v[204:205], off offset:256
	s_waitcnt lgkmcnt(0)
	v_add_co_u32_e32 v114, vcc, 0x20000, v202
	v_addc_co_u32_e32 v115, vcc, 0, v203, vcc
	global_load_dwordx4 v[118:121], v[114:115], off
	s_nop 0
	global_load_dwordx4 v[114:117], v[114:115], off offset:16
	s_waitcnt vmcnt(14)
	v_sub_f32_e32 v239, v239, v134
	v_sub_f32_e32 v238, v238, v134
	v_sub_f32_e32 v241, v241, v134
	v_sub_f32_e32 v240, v240, v134
	v_pk_mul_f32 v[240:241], v[132:133], v[240:241] op_sel_hi:[0,1]
	v_pk_mul_f32 v[238:239], v[132:133], v[238:239] op_sel_hi:[0,1]
	s_waitcnt vmcnt(13)
	v_sub_f32_e32 v235, v235, v134
	v_sub_f32_e32 v234, v234, v134
	v_sub_f32_e32 v237, v237, v134
	v_sub_f32_e32 v236, v236, v134
	v_pk_fma_f32 v[110:111], v[170:171], v[238:239], v[110:111]
	v_pk_fma_f32 v[112:113], v[162:163], v[240:241], v[112:113]
	v_pk_mul_f32 v[236:237], v[132:133], v[236:237] op_sel_hi:[0,1]
	v_pk_mul_f32 v[234:235], v[132:133], v[234:235] op_sel_hi:[0,1]
	v_pk_add_f32 v[112:113], v[186:187], v[112:113]
	v_pk_add_f32 v[110:111], v[188:189], v[110:111]
	v_pk_fma_f32 v[106:107], v[196:197], v[234:235], v[106:107]
	v_pk_fma_f32 v[108:109], v[194:195], v[236:237], v[108:109]
	v_pk_add_f32 v[106:107], v[192:193], v[106:107]
	v_pk_add_f32 v[108:109], v[190:191], v[108:109]
	v_add_f32_e32 v234, v110, v111
	v_add_f32_e32 v235, v112, v113
	v_add_f32_e32 v234, v234, v235
	v_add_f32_e32 v235, v106, v107
	v_add_f32_e32 v238, v108, v109
	v_add_f32_e32 v235, v235, v238
	v_add_f32_e32 v234, v234, v235
	v_add_f32_e32 v240, 0, v234
	v_mul_f32_e32 v234, v111, v111
	v_mul_f32_e32 v235, v113, v113
	v_fmac_f32_e32 v234, v110, v110
	v_fmac_f32_e32 v235, v112, v112
	v_add_co_u32_e32 v236, vcc, s4, v200
	v_add_f32_e32 v234, v234, v235
	v_mul_f32_e32 v235, v107, v107
	v_mul_f32_e32 v238, v109, v109
	v_addc_co_u32_e32 v237, vcc, 0, v201, vcc
	v_fmac_f32_e32 v235, v106, v106
	v_fmac_f32_e32 v238, v108, v108
	s_mov_b32 s1, 0x8000
	v_add_f32_e32 v235, v235, v238
	v_add_co_u32_e32 v238, vcc, s1, v198
	s_mov_b32 s1, 0x20000
	s_nop 0
	v_addc_co_u32_e32 v239, vcc, 0, v199, vcc
	v_add_f32_e32 v241, v234, v235
	s_mov_b64 s[24:25], 0x20000
	v_add_co_u32_e32 v234, vcc, s1, v202
	global_store_dwordx4 v[236:237], v[110:113], off nt
	global_store_dwordx4 v[236:237], v[106:109], off offset:16 nt
	v_addc_co_u32_e32 v235, vcc, 0, v203, vcc
	v_cvt_pk_bf16_f32 v110, v110, v111
	v_cvt_pk_bf16_f32 v111, v112, v113
	v_cvt_pk_bf16_f32 v112, v106, v107
	v_cvt_pk_bf16_f32 v113, v108, v109
	global_store_dwordx4 v[238:239], v[110:113], off
	v_lshl_add_u64 v[106:107], v[202:203], 0, s[24:25]
	s_nop 0
	v_add_co_u32_e32 v106, vcc, 0x20200, v202
	v_addc_co_u32_e32 v107, vcc, 0, v203, vcc
	global_load_dwordx4 v[110:113], v[106:107], off
	s_nop 0
	global_load_dwordx4 v[106:109], v[106:107], off offset:16
	s_waitcnt vmcnt(14)
; __device__ __forceinline__ unsigned cvt_pk_bf16(float lo, float hi) { unsigned r; asm volatile("v_cvt_pk_bf16_f32 %0, %1, %2" : "=v"(r) : "v"(lo), "v"(hi)); return r; }
; __device__ __forceinline__ void stats_mr(const f32x2 s, float& mu, float& r) { mu = s.x * (1.0f / 1024.0f); const float var = s.y * (1.0f / 1024.0f) - mu * mu; r = __builtin_amdgcn_rsqf(var + 1e-5f); }
;     __device__ __forceinline__ void operator()(const f32x4 (&acc)[2][2][4][2], const Unit& u, int wr, int wc, int fr, int fq) const {
;     ...
;         for (int g = 0; g < 8; ++g) { const int ai = g >> 2, m = g & 3; const int rr = ai * HALF + m * 16, rn = ((g + 1) >> 2) * HALF + ((g + 1) & 3) * 16;
;             f32x2 sv_n = sv_c; if (g + 1 < 8) sv_n = *(const f32x2*)(sp + (size_t)rn * 8 + ls);
;             float mu, r; stats_mr(sv_c, mu, r); float s1 = 0.f, s2 = 0.f;
; #pragma unroll
;             for (int bj = 0; bj < 2; ++bj) { const size_t ro = (size_t)rr * ldc + bj * HALF;
;                 f32x4 q0 = p0, q1 = p1;
;                 if (bj == 0) { q0 = *(const f32x4*)(bp + (ro + HALF) * 4 + l4); q1 = *(const f32x4*)(bp + (ro + HALF) * 4 + l4 + 16); }
;                 else if (g + 1 < 8) { q0 = *(const f32x4*)(bp + (size_t)rn * ldc * 4 + l4); q1 = *(const f32x4*)(bp + (size_t)rn * ldc * 4 + l4 + 16); }
;                 const f32x4 z0 = gv[bj][0] * ((p0 - mu) * r) + acc[ai][bj][m][0] + cv[bj][0], z1 = gv[bj][1] * ((p1 - mu) * r) + acc[ai][bj][m][1] + cv[bj][1];
;                 *(f32x4*)(op + ro * 4 + l4) = z0; *(f32x4*)(op + ro * 4 + l4 + 16) = z1;
;                 s1 += ((z0[0] + z0[1]) + (z0[2] + z0[3])) + ((z1[0] + z1[1]) + (z1[2] + z1[3]));
;                 s2 += ((z0[0] * z0[0] + z0[1] * z0[1]) + (z0[2] * z0[2] + z0[3] * z0[3])) + ((z1[0] * z1[0] + z1[1] * z1[1]) + (z1[2] * z1[2] + z1[3] * z1[3]));
;                 if (zb) { u32x4 w; w.x = cvt_pk_bf16(z0[0], z0[1]); w.y = cvt_pk_bf16(z0[2], z0[3]); w.z = cvt_pk_bf16(z1[0], z1[1]); w.w = cvt_pk_bf16(z1[2], z1[3]); *(u32x4*)(zp + ro * 2 + l2) = w; }
;                 p0 = q0; p1 = q1; }
;             s1 += __shfl_xor(s1, 16); s2 += __shfl_xor(s2, 16); s1 += __shfl_xor(s1, 32); s2 += __shfl_xor(s2, 32);
;             if (fq == 0) { atomicAdd(osp + 2 * (rr + fr), s1); atomicAdd(osp + 2 * (rr + fr) + 1, s2); }
;             sv_c = sv_n; }
	v_sub_f32_e32 v127, v127, v134
	v_sub_f32_e32 v126, v126, v134
	v_sub_f32_e32 v129, v129, v134
	v_sub_f32_e32 v128, v128, v134
	v_pk_mul_f32 v[128:129], v[132:133], v[128:129] op_sel_hi:[0,1]
	v_pk_mul_f32 v[126:127], v[132:133], v[126:127] op_sel_hi:[0,1]
	s_waitcnt vmcnt(13)
	v_sub_f32_e32 v123, v123, v134
	v_sub_f32_e32 v122, v122, v134
	v_sub_f32_e32 v125, v125, v134
	v_sub_f32_e32 v124, v124, v134
	v_pk_fma_f32 v[102:103], v[164:165], v[126:127], v[102:103]
	v_pk_fma_f32 v[104:105], v[160:161], v[128:129], v[104:105]
	v_pk_mul_f32 v[124:125], v[132:133], v[124:125] op_sel_hi:[0,1]
	v_pk_mul_f32 v[122:123], v[132:133], v[122:123] op_sel_hi:[0,1]
	v_pk_add_f32 v[104:105], v[174:175], v[104:105]
	v_pk_add_f32 v[102:103], v[176:177], v[102:103]
	v_pk_fma_f32 v[98:99], v[178:179], v[122:123], v[98:99]
	v_pk_fma_f32 v[100:101], v[172:173], v[124:125], v[100:101]
	v_pk_add_f32 v[98:99], v[168:169], v[98:99]
	v_pk_add_f32 v[100:101], v[166:167], v[100:101]
	v_add_f32_e32 v122, v102, v103
	v_add_f32_e32 v123, v104, v105
	v_add_f32_e32 v122, v122, v123
	v_add_f32_e32 v123, v98, v99
	v_add_f32_e32 v124, v100, v101
	v_add_f32_e32 v123, v123, v124
	v_add_f32_e32 v122, v122, v123
	v_mul_f32_e32 v123, v103, v103
	v_mul_f32_e32 v124, v105, v105
	v_fmac_f32_e32 v123, v102, v102
	v_fmac_f32_e32 v124, v104, v104
	v_add_f32_e32 v123, v123, v124
	v_mul_f32_e32 v124, v99, v99
	v_mul_f32_e32 v125, v101, v101
	v_fmac_f32_e32 v124, v98, v98
	v_fmac_f32_e32 v125, v100, v100
	v_add_f32_e32 v124, v124, v125
	v_add_f32_e32 v123, v123, v124
	v_add_f32_e32 v122, v240, v122
	v_add_f32_e32 v123, v241, v123
	global_store_dwordx4 v[236:237], v[102:105], off offset:512 nt
	global_store_dwordx4 v[236:237], v[98:101], off offset:528 nt
	s_nop 0
	v_cvt_pk_bf16_f32 v102, v102, v103
	v_cvt_pk_bf16_f32 v103, v104, v105
	v_cvt_pk_bf16_f32 v104, v98, v99
	ds_bpermute_b32 v98, v133, v122
	ds_bpermute_b32 v99, v133, v123
	v_cvt_pk_bf16_f32 v105, v100, v101
	global_store_dwordx4 v[238:239], v[102:105], off offset:256
	s_waitcnt lgkmcnt(1)
	v_add_f32_e32 v98, v122, v98
	s_waitcnt lgkmcnt(0)
	v_add_f32_e32 v99, v123, v99
	ds_bpermute_b32 v100, v136, v98
	ds_bpermute_b32 v101, v136, v99
	s_and_saveexec_b64 s[24:25], s[40:41]
	s_cbranch_execz .LBB0_734
	s_waitcnt lgkmcnt(1)
	v_add_f32_e32 v98, v98, v100
	s_waitcnt lgkmcnt(0)
	v_add_f32_e32 v99, v99, v101
	global_atomic_add_f32 v137, v98, s[82:83] offset:128
	global_atomic_add_f32 v137, v99, s[82:83] offset:132
.LBB0_734:
	s_or_b64 exec, exec, s[24:25]
	s_waitcnt vmcnt(12)
	v_pk_mul_f32 v[126:127], v[130:131], s[54:55] op_sel_hi:[1,0]
	s_mov_b64 s[24:25], 0x20200
	v_fma_f32 v98, -v126, v126, v127
	v_add_f32_e32 v98, 0x3727c5ac, v98
	v_rsq_f32_e32 v124, v98
	v_lshl_add_u64 v[98:99], v[202:203], 0, s[24:25]
	global_load_dwordx2 v[122:123], v[204:205], off offset:384
	s_waitcnt lgkmcnt(0)
	v_add_co_u32_e32 v98, vcc, 0x30000, v202
	v_addc_co_u32_e32 v99, vcc, 0, v203, vcc
	global_load_dwordx4 v[102:105], v[98:99], off
	s_nop 0
	global_load_dwordx4 v[98:101], v[98:99], off offset:16
	s_waitcnt vmcnt(14)
	v_sub_f32_e32 v119, v119, v126
	v_sub_f32_e32 v118, v118, v126
	v_sub_f32_e32 v121, v121, v126
	v_sub_f32_e32 v120, v120, v126
	v_pk_mul_f32 v[120:121], v[124:125], v[120:121] op_sel_hi:[0,1]
	v_pk_mul_f32 v[118:119], v[124:125], v[118:119] op_sel_hi:[0,1]
	s_waitcnt vmcnt(13)
	v_sub_f32_e32 v115, v115, v126
	v_sub_f32_e32 v114, v114, v126
	v_sub_f32_e32 v117, v117, v126
	v_sub_f32_e32 v116, v116, v126
	v_pk_fma_f32 v[94:95], v[170:171], v[118:119], v[94:95]
	v_pk_fma_f32 v[96:97], v[162:163], v[120:121], v[96:97]
	v_pk_mul_f32 v[116:117], v[124:125], v[116:117] op_sel_hi:[0,1]
	v_pk_mul_f32 v[114:115], v[124:125], v[114:115] op_sel_hi:[0,1]
	v_pk_add_f32 v[96:97], v[186:187], v[96:97]
	v_pk_add_f32 v[94:95], v[188:189], v[94:95]
	v_pk_fma_f32 v[90:91], v[196:197], v[114:115], v[90:91]
	v_pk_fma_f32 v[92:93], v[194:195], v[116:117], v[92:93]
	v_pk_add_f32 v[90:91], v[192:193], v[90:91]
	v_pk_add_f32 v[92:93], v[190:191], v[92:93]
	v_add_f32_e32 v114, v94, v95
	v_add_f32_e32 v115, v96, v97
	v_add_f32_e32 v114, v114, v115
	v_add_f32_e32 v115, v90, v91
	v_add_f32_e32 v118, v92, v93
	v_add_f32_e32 v115, v115, v118
	v_add_f32_e32 v114, v114, v115
	v_add_f32_e32 v120, 0, v114
	v_mul_f32_e32 v114, v95, v95
	v_mul_f32_e32 v115, v97, v97
	v_fmac_f32_e32 v114, v94, v94
	v_fmac_f32_e32 v115, v96, v96
	v_add_co_u32_e32 v116, vcc, s1, v200
	v_add_f32_e32 v114, v114, v115
	v_mul_f32_e32 v115, v91, v91
	v_mul_f32_e32 v118, v93, v93
	v_addc_co_u32_e32 v117, vcc, 0, v201, vcc
	v_fmac_f32_e32 v115, v90, v90
	v_fmac_f32_e32 v118, v92, v92
	v_add_f32_e32 v115, v115, v118
	v_add_co_u32_e32 v118, vcc, s4, v198
	s_mov_b32 s1, 0x30000
	s_nop 0
	v_addc_co_u32_e32 v119, vcc, 0, v199, vcc
	v_add_f32_e32 v121, v114, v115
	s_mov_b64 s[24:25], 0x30000
	v_add_co_u32_e32 v114, vcc, s1, v202
	global_store_dwordx4 v[116:117], v[94:97], off nt
	global_store_dwordx4 v[116:117], v[90:93], off offset:16 nt
	v_addc_co_u32_e32 v115, vcc, 0, v203, vcc
	v_cvt_pk_bf16_f32 v94, v94, v95
	v_cvt_pk_bf16_f32 v95, v96, v97
	v_cvt_pk_bf16_f32 v96, v90, v91
	v_cvt_pk_bf16_f32 v97, v92, v93
	global_store_dwordx4 v[118:119], v[94:97], off
	v_lshl_add_u64 v[90:91], v[202:203], 0, s[24:25]
	s_nop 0
	v_add_co_u32_e32 v90, vcc, 0x30200, v202
	v_addc_co_u32_e32 v91, vcc, 0, v203, vcc
	global_load_dwordx4 v[94:97], v[90:91], off
	s_nop 0
	global_load_dwordx4 v[90:93], v[90:91], off offset:16
	s_waitcnt vmcnt(14)
	v_sub_f32_e32 v111, v111, v126
	v_sub_f32_e32 v110, v110, v126
	v_sub_f32_e32 v113, v113, v126
	v_sub_f32_e32 v112, v112, v126
	v_pk_mul_f32 v[112:113], v[124:125], v[112:113] op_sel_hi:[0,1]
	v_pk_mul_f32 v[110:111], v[124:125], v[110:111] op_sel_hi:[0,1]
	s_waitcnt vmcnt(13)
; __device__ __forceinline__ unsigned cvt_pk_bf16(float lo, float hi) { unsigned r; asm volatile("v_cvt_pk_bf16_f32 %0, %1, %2" : "=v"(r) : "v"(lo), "v"(hi)); return r; }
; __device__ __forceinline__ void stats_mr(const f32x2 s, float& mu, float& r) { mu = s.x * (1.0f / 1024.0f); const float var = s.y * (1.0f / 1024.0f) - mu * mu; r = __builtin_amdgcn_rsqf(var + 1e-5f); }
;     __device__ __forceinline__ void operator()(const f32x4 (&acc)[2][2][4][2], const Unit& u, int wr, int wc, int fr, int fq) const {
;     ...
;         for (int g = 0; g < 8; ++g) { const int ai = g >> 2, m = g & 3; const int rr = ai * HALF + m * 16, rn = ((g + 1) >> 2) * HALF + ((g + 1) & 3) * 16;
;             f32x2 sv_n = sv_c; if (g + 1 < 8) sv_n = *(const f32x2*)(sp + (size_t)rn * 8 + ls);
;             float mu, r; stats_mr(sv_c, mu, r); float s1 = 0.f, s2 = 0.f;
; #pragma unroll
;             for (int bj = 0; bj < 2; ++bj) { const size_t ro = (size_t)rr * ldc + bj * HALF;
;                 f32x4 q0 = p0, q1 = p1;
;                 if (bj == 0) { q0 = *(const f32x4*)(bp + (ro + HALF) * 4 + l4); q1 = *(const f32x4*)(bp + (ro + HALF) * 4 + l4 + 16); }
;                 else if (g + 1 < 8) { q0 = *(const f32x4*)(bp + (size_t)rn * ldc * 4 + l4); q1 = *(const f32x4*)(bp + (size_t)rn * ldc * 4 + l4 + 16); }
;                 const f32x4 z0 = gv[bj][0] * ((p0 - mu) * r) + acc[ai][bj][m][0] + cv[bj][0], z1 = gv[bj][1] * ((p1 - mu) * r) + acc[ai][bj][m][1] + cv[bj][1];
;                 *(f32x4*)(op + ro * 4 + l4) = z0; *(f32x4*)(op + ro * 4 + l4 + 16) = z1;
;                 s1 += ((z0[0] + z0[1]) + (z0[2] + z0[3])) + ((z1[0] + z1[1]) + (z1[2] + z1[3]));
;                 s2 += ((z0[0] * z0[0] + z0[1] * z0[1]) + (z0[2] * z0[2] + z0[3] * z0[3])) + ((z1[0] * z1[0] + z1[1] * z1[1]) + (z1[2] * z1[2] + z1[3] * z1[3]));
;                 if (zb) { u32x4 w; w.x = cvt_pk_bf16(z0[0], z0[1]); w.y = cvt_pk_bf16(z0[2], z0[3]); w.z = cvt_pk_bf16(z1[0], z1[1]); w.w = cvt_pk_bf16(z1[2], z1[3]); *(u32x4*)(zp + ro * 2 + l2) = w; }
;                 p0 = q0; p1 = q1; }
;             s1 += __shfl_xor(s1, 16); s2 += __shfl_xor(s2, 16); s1 += __shfl_xor(s1, 32); s2 += __shfl_xor(s2, 32);
;             if (fq == 0) { atomicAdd(osp + 2 * (rr + fr), s1); atomicAdd(osp + 2 * (rr + fr) + 1, s2); }
;             sv_c = sv_n; }
	v_sub_f32_e32 v107, v107, v126
	v_sub_f32_e32 v106, v106, v126
	v_sub_f32_e32 v109, v109, v126
	v_sub_f32_e32 v108, v108, v126
	v_pk_fma_f32 v[86:87], v[164:165], v[110:111], v[86:87]
	v_pk_fma_f32 v[88:89], v[160:161], v[112:113], v[88:89]
	v_pk_mul_f32 v[108:109], v[124:125], v[108:109] op_sel_hi:[0,1]
	v_pk_mul_f32 v[106:107], v[124:125], v[106:107] op_sel_hi:[0,1]
	v_pk_add_f32 v[88:89], v[174:175], v[88:89]
	v_pk_add_f32 v[86:87], v[176:177], v[86:87]
	v_pk_fma_f32 v[82:83], v[178:179], v[106:107], v[82:83]
	v_pk_fma_f32 v[84:85], v[172:173], v[108:109], v[84:85]
	v_pk_add_f32 v[82:83], v[168:169], v[82:83]
	v_pk_add_f32 v[84:85], v[166:167], v[84:85]
	v_add_f32_e32 v106, v86, v87
	v_add_f32_e32 v107, v88, v89
	v_add_f32_e32 v106, v106, v107
	v_add_f32_e32 v107, v82, v83
	v_add_f32_e32 v108, v84, v85
	v_add_f32_e32 v107, v107, v108
	v_add_f32_e32 v106, v106, v107
	v_mul_f32_e32 v107, v87, v87
	v_mul_f32_e32 v108, v89, v89
	v_fmac_f32_e32 v107, v86, v86
	v_fmac_f32_e32 v108, v88, v88
	v_add_f32_e32 v107, v107, v108
	v_mul_f32_e32 v108, v83, v83
	v_mul_f32_e32 v109, v85, v85
	v_fmac_f32_e32 v108, v82, v82
	v_fmac_f32_e32 v109, v84, v84
	v_add_f32_e32 v108, v108, v109
	v_add_f32_e32 v107, v107, v108
	v_add_f32_e32 v106, v120, v106
	v_add_f32_e32 v107, v121, v107
	global_store_dwordx4 v[116:117], v[86:89], off offset:512 nt
	global_store_dwordx4 v[116:117], v[82:85], off offset:528 nt
	s_nop 0
	v_cvt_pk_bf16_f32 v86, v86, v87
	v_cvt_pk_bf16_f32 v87, v88, v89
	v_cvt_pk_bf16_f32 v88, v82, v83
	ds_bpermute_b32 v82, v133, v106
	ds_bpermute_b32 v83, v133, v107
	v_cvt_pk_bf16_f32 v89, v84, v85
	global_store_dwordx4 v[118:119], v[86:89], off offset:256
	s_waitcnt lgkmcnt(1)
	v_add_f32_e32 v82, v106, v82
	s_waitcnt lgkmcnt(0)
	v_add_f32_e32 v83, v107, v83
	ds_bpermute_b32 v84, v136, v82
	ds_bpermute_b32 v85, v136, v83
	s_and_saveexec_b64 s[24:25], s[40:41]
	s_cbranch_execz .LBB0_736
	s_waitcnt lgkmcnt(1)
	v_add_f32_e32 v82, v82, v84
	s_waitcnt lgkmcnt(0)
	v_add_f32_e32 v83, v83, v85
	global_atomic_add_f32 v137, v82, s[82:83] offset:256
	global_atomic_add_f32 v137, v83, s[82:83] offset:260
.LBB0_736:
	s_or_b64 exec, exec, s[24:25]
	s_waitcnt vmcnt(12)
	v_pk_mul_f32 v[110:111], v[122:123], s[54:55] op_sel_hi:[1,0]
	s_mov_b64 s[24:25], 0x30200
	v_fma_f32 v82, -v110, v110, v111
	v_add_f32_e32 v82, 0x3727c5ac, v82
	v_rsq_f32_e32 v108, v82
	v_lshl_add_u64 v[82:83], v[202:203], 0, s[24:25]
	global_load_dwordx2 v[106:107], v[204:205], off offset:1024
	s_waitcnt lgkmcnt(0)
	v_add_co_u32_e32 v82, vcc, 0x80000, v202
	v_addc_co_u32_e32 v83, vcc, 0, v203, vcc
	global_load_dwordx4 v[86:89], v[82:83], off
	s_nop 0
	global_load_dwordx4 v[82:85], v[82:83], off offset:16
	s_waitcnt vmcnt(14)
	v_sub_f32_e32 v103, v103, v110
	v_sub_f32_e32 v102, v102, v110
	v_sub_f32_e32 v105, v105, v110
	v_sub_f32_e32 v104, v104, v110
	v_pk_mul_f32 v[104:105], v[108:109], v[104:105] op_sel_hi:[0,1]
	v_pk_mul_f32 v[102:103], v[108:109], v[102:103] op_sel_hi:[0,1]
	s_waitcnt vmcnt(13)
	v_sub_f32_e32 v99, v99, v110
	v_sub_f32_e32 v98, v98, v110
	v_sub_f32_e32 v101, v101, v110
	v_sub_f32_e32 v100, v100, v110
	v_pk_fma_f32 v[78:79], v[170:171], v[102:103], v[78:79]
	v_pk_fma_f32 v[80:81], v[162:163], v[104:105], v[80:81]
	v_pk_mul_f32 v[100:101], v[108:109], v[100:101] op_sel_hi:[0,1]
	v_pk_mul_f32 v[98:99], v[108:109], v[98:99] op_sel_hi:[0,1]
	v_pk_add_f32 v[80:81], v[186:187], v[80:81]
	v_pk_add_f32 v[78:79], v[188:189], v[78:79]
	v_pk_fma_f32 v[74:75], v[196:197], v[98:99], v[74:75]
	v_pk_fma_f32 v[76:77], v[194:195], v[100:101], v[76:77]
	v_pk_add_f32 v[74:75], v[192:193], v[74:75]
	v_pk_add_f32 v[76:77], v[190:191], v[76:77]
	v_add_f32_e32 v98, v78, v79
	v_add_f32_e32 v99, v80, v81
	v_add_f32_e32 v98, v98, v99
	v_add_f32_e32 v99, v74, v75
	v_add_f32_e32 v102, v76, v77
	v_add_f32_e32 v99, v99, v102
	v_add_f32_e32 v98, v98, v99
	v_add_f32_e32 v104, 0, v98
	v_mul_f32_e32 v98, v79, v79
	v_mul_f32_e32 v99, v81, v81
	v_fmac_f32_e32 v98, v78, v78
	v_fmac_f32_e32 v99, v80, v80
	v_add_co_u32_e32 v100, vcc, s1, v200
	v_add_f32_e32 v98, v98, v99
	v_mul_f32_e32 v99, v75, v75
	v_mul_f32_e32 v102, v77, v77
	v_addc_co_u32_e32 v101, vcc, 0, v201, vcc
	v_fmac_f32_e32 v99, v74, v74
	v_fmac_f32_e32 v102, v76, v76
	s_mov_b32 s1, 0x18000
	v_add_f32_e32 v99, v99, v102
	v_add_co_u32_e32 v102, vcc, s1, v198
	s_mov_b32 s1, 0x80000
	s_nop 0
	v_addc_co_u32_e32 v103, vcc, 0, v199, vcc
	v_add_f32_e32 v105, v98, v99
	s_mov_b64 s[24:25], 0x80000
	v_add_co_u32_e32 v98, vcc, s1, v202
	global_store_dwordx4 v[100:101], v[78:81], off nt
	global_store_dwordx4 v[100:101], v[74:77], off offset:16 nt
	v_addc_co_u32_e32 v99, vcc, 0, v203, vcc
	v_cvt_pk_bf16_f32 v78, v78, v79
	v_cvt_pk_bf16_f32 v79, v80, v81
	v_cvt_pk_bf16_f32 v80, v74, v75
	v_cvt_pk_bf16_f32 v81, v76, v77
	global_store_dwordx4 v[102:103], v[78:81], off
	v_lshl_add_u64 v[74:75], v[202:203], 0, s[24:25]
	s_nop 0
	v_add_co_u32_e32 v74, vcc, 0x80200, v202
	v_addc_co_u32_e32 v75, vcc, 0, v203, vcc
	global_load_dwordx4 v[78:81], v[74:75], off
	s_nop 0
	global_load_dwordx4 v[74:77], v[74:75], off offset:16
	s_waitcnt vmcnt(14)
	v_sub_f32_e32 v95, v95, v110
	v_sub_f32_e32 v94, v94, v110
	v_sub_f32_e32 v97, v97, v110
	v_sub_f32_e32 v96, v96, v110
	v_pk_mul_f32 v[96:97], v[108:109], v[96:97] op_sel_hi:[0,1]
	v_pk_mul_f32 v[94:95], v[108:109], v[94:95] op_sel_hi:[0,1]
	s_waitcnt vmcnt(13)
; __device__ __forceinline__ unsigned cvt_pk_bf16(float lo, float hi) { unsigned r; asm volatile("v_cvt_pk_bf16_f32 %0, %1, %2" : "=v"(r) : "v"(lo), "v"(hi)); return r; }
; __device__ __forceinline__ void stats_mr(const f32x2 s, float& mu, float& r) { mu = s.x * (1.0f / 1024.0f); const float var = s.y * (1.0f / 1024.0f) - mu * mu; r = __builtin_amdgcn_rsqf(var + 1e-5f); }
;     __device__ __forceinline__ void operator()(const f32x4 (&acc)[2][2][4][2], const Unit& u, int wr, int wc, int fr, int fq) const {
;     ...
;         for (int g = 0; g < 8; ++g) { const int ai = g >> 2, m = g & 3; const int rr = ai * HALF + m * 16, rn = ((g + 1) >> 2) * HALF + ((g + 1) & 3) * 16;
;             f32x2 sv_n = sv_c; if (g + 1 < 8) sv_n = *(const f32x2*)(sp + (size_t)rn * 8 + ls);
;             float mu, r; stats_mr(sv_c, mu, r); float s1 = 0.f, s2 = 0.f;
; #pragma unroll
;             for (int bj = 0; bj < 2; ++bj) { const size_t ro = (size_t)rr * ldc + bj * HALF;
;                 f32x4 q0 = p0, q1 = p1;
;                 if (bj == 0) { q0 = *(const f32x4*)(bp + (ro + HALF) * 4 + l4); q1 = *(const f32x4*)(bp + (ro + HALF) * 4 + l4 + 16); }
;                 else if (g + 1 < 8) { q0 = *(const f32x4*)(bp + (size_t)rn * ldc * 4 + l4); q1 = *(const f32x4*)(bp + (size_t)rn * ldc * 4 + l4 + 16); }
;                 const f32x4 z0 = gv[bj][0] * ((p0 - mu) * r) + acc[ai][bj][m][0] + cv[bj][0], z1 = gv[bj][1] * ((p1 - mu) * r) + acc[ai][bj][m][1] + cv[bj][1];
;                 *(f32x4*)(op + ro * 4 + l4) = z0; *(f32x4*)(op + ro * 4 + l4 + 16) = z1;
;                 s1 += ((z0[0] + z0[1]) + (z0[2] + z0[3])) + ((z1[0] + z1[1]) + (z1[2] + z1[3]));
;                 s2 += ((z0[0] * z0[0] + z0[1] * z0[1]) + (z0[2] * z0[2] + z0[3] * z0[3])) + ((z1[0] * z1[0] + z1[1] * z1[1]) + (z1[2] * z1[2] + z1[3] * z1[3]));
;                 if (zb) { u32x4 w; w.x = cvt_pk_bf16(z0[0], z0[1]); w.y = cvt_pk_bf16(z0[2], z0[3]); w.z = cvt_pk_bf16(z1[0], z1[1]); w.w = cvt_pk_bf16(z1[2], z1[3]); *(u32x4*)(zp + ro * 2 + l2) = w; }
;                 p0 = q0; p1 = q1; }
;             s1 += __shfl_xor(s1, 16); s2 += __shfl_xor(s2, 16); s1 += __shfl_xor(s1, 32); s2 += __shfl_xor(s2, 32);
;             if (fq == 0) { atomicAdd(osp + 2 * (rr + fr), s1); atomicAdd(osp + 2 * (rr + fr) + 1, s2); }
;             sv_c = sv_n; }
	v_sub_f32_e32 v91, v91, v110
	v_sub_f32_e32 v90, v90, v110
	v_sub_f32_e32 v93, v93, v110
	v_sub_f32_e32 v92, v92, v110
	v_pk_fma_f32 v[70:71], v[164:165], v[94:95], v[70:71]
	v_pk_fma_f32 v[72:73], v[160:161], v[96:97], v[72:73]
	v_pk_mul_f32 v[92:93], v[108:109], v[92:93] op_sel_hi:[0,1]
	v_pk_mul_f32 v[90:91], v[108:109], v[90:91] op_sel_hi:[0,1]
	v_pk_add_f32 v[72:73], v[174:175], v[72:73]
	v_pk_add_f32 v[70:71], v[176:177], v[70:71]
	v_pk_fma_f32 v[66:67], v[178:179], v[90:91], v[66:67]
	v_pk_fma_f32 v[68:69], v[172:173], v[92:93], v[68:69]
	v_pk_add_f32 v[66:67], v[168:169], v[66:67]
	v_pk_add_f32 v[68:69], v[166:167], v[68:69]
	v_add_f32_e32 v90, v70, v71
	v_add_f32_e32 v91, v72, v73
	v_add_f32_e32 v90, v90, v91
	v_add_f32_e32 v91, v66, v67
	v_add_f32_e32 v92, v68, v69
	v_add_f32_e32 v91, v91, v92
	v_add_f32_e32 v90, v90, v91
	v_mul_f32_e32 v91, v71, v71
	v_mul_f32_e32 v92, v73, v73
	v_fmac_f32_e32 v91, v70, v70
	v_fmac_f32_e32 v92, v72, v72
	v_add_f32_e32 v91, v91, v92
	v_mul_f32_e32 v92, v67, v67
	v_mul_f32_e32 v93, v69, v69
	v_fmac_f32_e32 v92, v66, v66
	v_fmac_f32_e32 v93, v68, v68
	v_add_f32_e32 v92, v92, v93
	v_add_f32_e32 v91, v91, v92
	v_add_f32_e32 v90, v104, v90
	v_add_f32_e32 v91, v105, v91
	global_store_dwordx4 v[100:101], v[70:73], off offset:512 nt
	global_store_dwordx4 v[100:101], v[66:69], off offset:528 nt
	s_nop 0
	v_cvt_pk_bf16_f32 v70, v70, v71
	v_cvt_pk_bf16_f32 v71, v72, v73
	v_cvt_pk_bf16_f32 v72, v66, v67
	ds_bpermute_b32 v66, v133, v90
	ds_bpermute_b32 v67, v133, v91
	v_cvt_pk_bf16_f32 v73, v68, v69
	global_store_dwordx4 v[102:103], v[70:73], off offset:256
	s_waitcnt lgkmcnt(1)
	v_add_f32_e32 v66, v90, v66
	s_waitcnt lgkmcnt(0)
	v_add_f32_e32 v67, v91, v67
	ds_bpermute_b32 v68, v136, v66
	ds_bpermute_b32 v69, v136, v67
	s_and_saveexec_b64 s[24:25], s[40:41]
	s_cbranch_execz .LBB0_738
	s_waitcnt lgkmcnt(1)
	v_add_f32_e32 v66, v66, v68
	s_waitcnt lgkmcnt(0)
	v_add_f32_e32 v67, v67, v69
	global_atomic_add_f32 v137, v66, s[82:83] offset:384
	global_atomic_add_f32 v137, v67, s[82:83] offset:388
.LBB0_738:
	s_or_b64 exec, exec, s[24:25]
	s_waitcnt vmcnt(12)
	v_pk_mul_f32 v[94:95], v[106:107], s[54:55] op_sel_hi:[1,0]
	s_mov_b64 s[24:25], 0x80200
	v_fma_f32 v66, -v94, v94, v95
	v_add_f32_e32 v66, 0x3727c5ac, v66
	v_rsq_f32_e32 v92, v66
	v_lshl_add_u64 v[66:67], v[202:203], 0, s[24:25]
	global_load_dwordx2 v[90:91], v[204:205], off offset:1152
	s_waitcnt lgkmcnt(0)
	v_add_co_u32_e32 v66, vcc, 0x90000, v202
	v_addc_co_u32_e32 v67, vcc, 0, v203, vcc
	global_load_dwordx4 v[70:73], v[66:67], off
	s_nop 0
	global_load_dwordx4 v[66:69], v[66:67], off offset:16
	s_waitcnt vmcnt(14)
	v_sub_f32_e32 v87, v87, v94
	v_sub_f32_e32 v86, v86, v94
	v_sub_f32_e32 v89, v89, v94
	v_sub_f32_e32 v88, v88, v94
	v_pk_mul_f32 v[88:89], v[92:93], v[88:89] op_sel_hi:[0,1]
	v_pk_mul_f32 v[86:87], v[92:93], v[86:87] op_sel_hi:[0,1]
	s_waitcnt vmcnt(13)
	v_sub_f32_e32 v83, v83, v94
	v_sub_f32_e32 v82, v82, v94
	v_sub_f32_e32 v85, v85, v94
	v_sub_f32_e32 v84, v84, v94
	v_pk_fma_f32 v[62:63], v[170:171], v[86:87], v[62:63]
	v_pk_fma_f32 v[64:65], v[162:163], v[88:89], v[64:65]
	v_pk_mul_f32 v[84:85], v[92:93], v[84:85] op_sel_hi:[0,1]
	v_pk_mul_f32 v[82:83], v[92:93], v[82:83] op_sel_hi:[0,1]
	v_pk_add_f32 v[64:65], v[186:187], v[64:65]
	v_pk_add_f32 v[62:63], v[188:189], v[62:63]
	v_pk_fma_f32 v[58:59], v[196:197], v[82:83], v[58:59]
	v_pk_fma_f32 v[60:61], v[194:195], v[84:85], v[60:61]
	v_pk_add_f32 v[58:59], v[192:193], v[58:59]
	v_pk_add_f32 v[60:61], v[190:191], v[60:61]
	v_add_f32_e32 v82, v62, v63
	v_add_f32_e32 v83, v64, v65
	v_add_f32_e32 v82, v82, v83
	v_add_f32_e32 v83, v58, v59
	v_add_f32_e32 v86, v60, v61
	v_add_f32_e32 v83, v83, v86
	v_add_f32_e32 v82, v82, v83
	v_add_f32_e32 v88, 0, v82
	v_mul_f32_e32 v82, v63, v63
	v_mul_f32_e32 v83, v65, v65
	v_fmac_f32_e32 v82, v62, v62
	v_fmac_f32_e32 v83, v64, v64
	v_add_co_u32_e32 v84, vcc, s1, v200
	v_add_f32_e32 v82, v82, v83
	v_mul_f32_e32 v83, v59, v59
	v_mul_f32_e32 v86, v61, v61
	v_addc_co_u32_e32 v85, vcc, 0, v201, vcc
	v_fmac_f32_e32 v83, v58, v58
	v_fmac_f32_e32 v86, v60, v60
	s_mov_b32 s1, 0x40000
	v_add_f32_e32 v83, v83, v86
	v_add_co_u32_e32 v86, vcc, s1, v198
	v_add_f32_e32 v89, v82, v83
	s_nop 0
	v_addc_co_u32_e32 v87, vcc, 0, v199, vcc
	v_add_co_u32_e32 v82, vcc, s5, v202
	global_store_dwordx4 v[84:85], v[62:65], off nt
	global_store_dwordx4 v[84:85], v[58:61], off offset:16 nt
	v_addc_co_u32_e32 v83, vcc, 0, v203, vcc
	v_cvt_pk_bf16_f32 v62, v62, v63
	v_cvt_pk_bf16_f32 v63, v64, v65
	v_cvt_pk_bf16_f32 v64, v58, v59
	v_cvt_pk_bf16_f32 v65, v60, v61
	global_store_dwordx4 v[86:87], v[62:65], off
	v_lshl_add_u64 v[58:59], v[202:203], 0, s[28:29]
	s_nop 0
	v_add_co_u32_e32 v58, vcc, 0x90200, v202
	v_addc_co_u32_e32 v59, vcc, 0, v203, vcc
	global_load_dwordx4 v[62:65], v[58:59], off
	s_nop 0
	global_load_dwordx4 v[58:61], v[58:59], off offset:16
	s_waitcnt vmcnt(14)
	v_sub_f32_e32 v79, v79, v94
	v_sub_f32_e32 v78, v78, v94
	v_sub_f32_e32 v81, v81, v94
	v_sub_f32_e32 v80, v80, v94
	v_pk_mul_f32 v[80:81], v[92:93], v[80:81] op_sel_hi:[0,1]
	v_pk_mul_f32 v[78:79], v[92:93], v[78:79] op_sel_hi:[0,1]
	s_waitcnt vmcnt(13)
	v_sub_f32_e32 v75, v75, v94
	v_sub_f32_e32 v74, v74, v94
	v_sub_f32_e32 v77, v77, v94
	v_sub_f32_e32 v76, v76, v94
	v_pk_fma_f32 v[54:55], v[164:165], v[78:79], v[54:55]
	v_pk_fma_f32 v[56:57], v[160:161], v[80:81], v[56:57]
	v_pk_mul_f32 v[76:77], v[92:93], v[76:77] op_sel_hi:[0,1]
	v_pk_mul_f32 v[74:75], v[92:93], v[74:75] op_sel_hi:[0,1]
	v_pk_add_f32 v[56:57], v[174:175], v[56:57]
	v_pk_add_f32 v[54:55], v[176:177], v[54:55]
	v_pk_fma_f32 v[50:51], v[178:179], v[74:75], v[50:51]
	v_pk_fma_f32 v[52:53], v[172:173], v[76:77], v[52:53]
	v_pk_add_f32 v[50:51], v[168:169], v[50:51]
	v_pk_add_f32 v[52:53], v[166:167], v[52:53]
	v_add_f32_e32 v74, v54, v55
	v_add_f32_e32 v75, v56, v57
	v_add_f32_e32 v74, v74, v75
	v_add_f32_e32 v75, v50, v51
	v_add_f32_e32 v76, v52, v53
	v_add_f32_e32 v75, v75, v76
	v_add_f32_e32 v74, v74, v75
	v_mul_f32_e32 v75, v55, v55
	v_mul_f32_e32 v76, v57, v57
	v_fmac_f32_e32 v75, v54, v54
	v_fmac_f32_e32 v76, v56, v56
	v_add_f32_e32 v75, v75, v76
	v_mul_f32_e32 v76, v51, v51
	v_mul_f32_e32 v77, v53, v53
	v_fmac_f32_e32 v76, v50, v50
	v_fmac_f32_e32 v77, v52, v52
	v_add_f32_e32 v76, v76, v77
	v_add_f32_e32 v75, v75, v76
	v_add_f32_e32 v74, v88, v74
	v_add_f32_e32 v75, v89, v75
	global_store_dwordx4 v[84:85], v[54:57], off offset:512 nt
	global_store_dwordx4 v[84:85], v[50:53], off offset:528 nt
	s_nop 0
	v_cvt_pk_bf16_f32 v54, v54, v55
	v_cvt_pk_bf16_f32 v55, v56, v57
	v_cvt_pk_bf16_f32 v56, v50, v51
	ds_bpermute_b32 v50, v133, v74
	ds_bpermute_b32 v51, v133, v75
	v_cvt_pk_bf16_f32 v57, v52, v53
	global_store_dwordx4 v[86:87], v[54:57], off offset:256
	s_waitcnt lgkmcnt(1)
	v_add_f32_e32 v50, v74, v50
	s_waitcnt lgkmcnt(0)
	v_add_f32_e32 v51, v75, v51
	ds_bpermute_b32 v52, v136, v50
	ds_bpermute_b32 v53, v136, v51
	s_and_saveexec_b64 s[24:25], s[40:41]
	s_cbranch_execz .LBB0_740
; __device__ __forceinline__ unsigned cvt_pk_bf16(float lo, float hi) { unsigned r; asm volatile("v_cvt_pk_bf16_f32 %0, %1, %2" : "=v"(r) : "v"(lo), "v"(hi)); return r; }
; __device__ __forceinline__ void stats_mr(const f32x2 s, float& mu, float& r) { mu = s.x * (1.0f / 1024.0f); const float var = s.y * (1.0f / 1024.0f) - mu * mu; r = __builtin_amdgcn_rsqf(var + 1e-5f); }
;     __device__ __forceinline__ void operator()(const f32x4 (&acc)[2][2][4][2], const Unit& u, int wr, int wc, int fr, int fq) const {
;     ...
;         for (int g = 0; g < 8; ++g) { const int ai = g >> 2, m = g & 3; const int rr = ai * HALF + m * 16, rn = ((g + 1) >> 2) * HALF + ((g + 1) & 3) * 16;
;             f32x2 sv_n = sv_c; if (g + 1 < 8) sv_n = *(const f32x2*)(sp + (size_t)rn * 8 + ls);
;             float mu, r; stats_mr(sv_c, mu, r); float s1 = 0.f, s2 = 0.f;
; #pragma unroll
;             for (int bj = 0; bj < 2; ++bj) { const size_t ro = (size_t)rr * ldc + bj * HALF;
;                 f32x4 q0 = p0, q1 = p1;
;                 if (bj == 0) { q0 = *(const f32x4*)(bp + (ro + HALF) * 4 + l4); q1 = *(const f32x4*)(bp + (ro + HALF) * 4 + l4 + 16); }
;                 else if (g + 1 < 8) { q0 = *(const f32x4*)(bp + (size_t)rn * ldc * 4 + l4); q1 = *(const f32x4*)(bp + (size_t)rn * ldc * 4 + l4 + 16); }
;                 const f32x4 z0 = gv[bj][0] * ((p0 - mu) * r) + acc[ai][bj][m][0] + cv[bj][0], z1 = gv[bj][1] * ((p1 - mu) * r) + acc[ai][bj][m][1] + cv[bj][1];
;                 *(f32x4*)(op + ro * 4 + l4) = z0; *(f32x4*)(op + ro * 4 + l4 + 16) = z1;
;                 s1 += ((z0[0] + z0[1]) + (z0[2] + z0[3])) + ((z1[0] + z1[1]) + (z1[2] + z1[3]));
;                 s2 += ((z0[0] * z0[0] + z0[1] * z0[1]) + (z0[2] * z0[2] + z0[3] * z0[3])) + ((z1[0] * z1[0] + z1[1] * z1[1]) + (z1[2] * z1[2] + z1[3] * z1[3]));
;                 if (zb) { u32x4 w; w.x = cvt_pk_bf16(z0[0], z0[1]); w.y = cvt_pk_bf16(z0[2], z0[3]); w.z = cvt_pk_bf16(z1[0], z1[1]); w.w = cvt_pk_bf16(z1[2], z1[3]); *(u32x4*)(zp + ro * 2 + l2) = w; }
;                 p0 = q0; p1 = q1; }
;             s1 += __shfl_xor(s1, 16); s2 += __shfl_xor(s2, 16); s1 += __shfl_xor(s1, 32); s2 += __shfl_xor(s2, 32);
;             if (fq == 0) { atomicAdd(osp + 2 * (rr + fr), s1); atomicAdd(osp + 2 * (rr + fr) + 1, s2); }
;             sv_c = sv_n; }
	s_waitcnt lgkmcnt(1)
	v_add_f32_e32 v50, v50, v52
	s_waitcnt lgkmcnt(0)
	v_add_f32_e32 v51, v51, v53
	global_atomic_add_f32 v137, v50, s[82:83] offset:1024
	global_atomic_add_f32 v137, v51, s[82:83] offset:1028
.LBB0_740:
	s_or_b64 exec, exec, s[24:25]
	s_waitcnt vmcnt(12)
	v_pk_mul_f32 v[78:79], v[90:91], s[54:55] op_sel_hi:[1,0]
	s_mov_b64 s[24:25], 0x90200
	v_fma_f32 v50, -v78, v78, v79
	v_add_f32_e32 v50, 0x3727c5ac, v50
	v_rsq_f32_e32 v76, v50
	v_lshl_add_u64 v[50:51], v[202:203], 0, s[24:25]
	global_load_dwordx2 v[74:75], v[204:205], off offset:1280
	s_waitcnt lgkmcnt(0)
	v_add_co_u32_e32 v50, vcc, 0xa0000, v202
	v_addc_co_u32_e32 v51, vcc, 0, v203, vcc
	global_load_dwordx4 v[54:57], v[50:51], off
	s_nop 0
	global_load_dwordx4 v[50:53], v[50:51], off offset:16
	s_waitcnt vmcnt(14)
	v_sub_f32_e32 v71, v71, v78
	v_sub_f32_e32 v70, v70, v78
	v_sub_f32_e32 v73, v73, v78
	v_sub_f32_e32 v72, v72, v78
	v_pk_mul_f32 v[72:73], v[76:77], v[72:73] op_sel_hi:[0,1]
	v_pk_mul_f32 v[70:71], v[76:77], v[70:71] op_sel_hi:[0,1]
	s_waitcnt vmcnt(13)
	v_sub_f32_e32 v67, v67, v78
	v_sub_f32_e32 v66, v66, v78
	v_sub_f32_e32 v69, v69, v78
	v_sub_f32_e32 v68, v68, v78
	v_pk_fma_f32 v[46:47], v[170:171], v[70:71], v[46:47]
	v_pk_fma_f32 v[48:49], v[162:163], v[72:73], v[48:49]
	v_pk_mul_f32 v[68:69], v[76:77], v[68:69] op_sel_hi:[0,1]
	v_pk_mul_f32 v[66:67], v[76:77], v[66:67] op_sel_hi:[0,1]
	v_pk_add_f32 v[48:49], v[186:187], v[48:49]
	v_pk_add_f32 v[46:47], v[188:189], v[46:47]
	v_pk_fma_f32 v[42:43], v[196:197], v[66:67], v[42:43]
	v_pk_fma_f32 v[44:45], v[194:195], v[68:69], v[44:45]
	v_pk_add_f32 v[42:43], v[192:193], v[42:43]
	v_pk_add_f32 v[44:45], v[190:191], v[44:45]
	v_add_f32_e32 v66, v46, v47
	v_add_f32_e32 v67, v48, v49
	v_add_f32_e32 v66, v66, v67
	v_add_f32_e32 v67, v42, v43
	v_add_f32_e32 v70, v44, v45
	v_add_f32_e32 v67, v67, v70
	v_add_f32_e32 v66, v66, v67
	v_add_f32_e32 v72, 0, v66
	v_mul_f32_e32 v66, v47, v47
	v_mul_f32_e32 v67, v49, v49
	v_fmac_f32_e32 v66, v46, v46
	v_fmac_f32_e32 v67, v48, v48
	v_add_co_u32_e32 v68, vcc, s5, v200
	v_add_f32_e32 v66, v66, v67
	v_mul_f32_e32 v67, v43, v43
	v_mul_f32_e32 v70, v45, v45
	v_addc_co_u32_e32 v69, vcc, 0, v201, vcc
	v_fmac_f32_e32 v67, v42, v42
	v_fmac_f32_e32 v70, v44, v44
	s_mov_b32 s1, 0x48000
	v_add_f32_e32 v67, v67, v70
	v_add_co_u32_e32 v70, vcc, s1, v198
	s_mov_b32 s1, 0xa0000
	s_nop 0
	v_addc_co_u32_e32 v71, vcc, 0, v199, vcc
	v_add_f32_e32 v73, v66, v67
	s_mov_b64 s[4:5], 0xa0000
	v_add_co_u32_e32 v66, vcc, s1, v202
	global_store_dwordx4 v[68:69], v[46:49], off nt
	global_store_dwordx4 v[68:69], v[42:45], off offset:16 nt
	v_addc_co_u32_e32 v67, vcc, 0, v203, vcc
	v_cvt_pk_bf16_f32 v46, v46, v47
	v_cvt_pk_bf16_f32 v47, v48, v49
	v_cvt_pk_bf16_f32 v48, v42, v43
	v_cvt_pk_bf16_f32 v49, v44, v45
	global_store_dwordx4 v[70:71], v[46:49], off
	v_lshl_add_u64 v[42:43], v[202:203], 0, s[4:5]
	s_nop 0
	v_add_co_u32_e32 v42, vcc, 0xa0200, v202
	v_addc_co_u32_e32 v43, vcc, 0, v203, vcc
	global_load_dwordx4 v[46:49], v[42:43], off
	s_nop 0
	global_load_dwordx4 v[42:45], v[42:43], off offset:16
	s_waitcnt vmcnt(14)
	v_sub_f32_e32 v63, v63, v78
	v_sub_f32_e32 v62, v62, v78
	v_sub_f32_e32 v65, v65, v78
	v_sub_f32_e32 v64, v64, v78
	v_pk_mul_f32 v[64:65], v[76:77], v[64:65] op_sel_hi:[0,1]
	v_pk_mul_f32 v[62:63], v[76:77], v[62:63] op_sel_hi:[0,1]
	s_waitcnt vmcnt(13)
	v_sub_f32_e32 v59, v59, v78
	v_sub_f32_e32 v58, v58, v78
	v_sub_f32_e32 v61, v61, v78
	v_sub_f32_e32 v60, v60, v78
	v_pk_fma_f32 v[38:39], v[164:165], v[62:63], v[38:39]
	v_pk_fma_f32 v[40:41], v[160:161], v[64:65], v[40:41]
	v_pk_mul_f32 v[60:61], v[76:77], v[60:61] op_sel_hi:[0,1]
	v_pk_mul_f32 v[58:59], v[76:77], v[58:59] op_sel_hi:[0,1]
	v_pk_add_f32 v[40:41], v[174:175], v[40:41]
	v_pk_add_f32 v[38:39], v[176:177], v[38:39]
	v_pk_fma_f32 v[34:35], v[178:179], v[58:59], v[34:35]
	v_pk_fma_f32 v[36:37], v[172:173], v[60:61], v[36:37]
	v_pk_add_f32 v[34:35], v[168:169], v[34:35]
	v_pk_add_f32 v[36:37], v[166:167], v[36:37]
	v_add_f32_e32 v58, v38, v39
	v_add_f32_e32 v59, v40, v41
	v_add_f32_e32 v58, v58, v59
	v_add_f32_e32 v59, v34, v35
	v_add_f32_e32 v60, v36, v37
	v_add_f32_e32 v59, v59, v60
	v_add_f32_e32 v58, v58, v59
	v_mul_f32_e32 v59, v39, v39
	v_mul_f32_e32 v60, v41, v41
	v_fmac_f32_e32 v59, v38, v38
	v_fmac_f32_e32 v60, v40, v40
	v_add_f32_e32 v59, v59, v60
	v_mul_f32_e32 v60, v35, v35
	v_mul_f32_e32 v61, v37, v37
	v_fmac_f32_e32 v60, v34, v34
	v_fmac_f32_e32 v61, v36, v36
	v_add_f32_e32 v60, v60, v61
	v_add_f32_e32 v59, v59, v60
	v_add_f32_e32 v58, v72, v58
	v_add_f32_e32 v59, v73, v59
	global_store_dwordx4 v[68:69], v[38:41], off offset:512 nt
	global_store_dwordx4 v[68:69], v[34:37], off offset:528 nt
	s_nop 0
	v_cvt_pk_bf16_f32 v38, v38, v39
	v_cvt_pk_bf16_f32 v39, v40, v41
	v_cvt_pk_bf16_f32 v40, v34, v35
	ds_bpermute_b32 v34, v133, v58
	ds_bpermute_b32 v35, v133, v59
	v_cvt_pk_bf16_f32 v41, v36, v37
	global_store_dwordx4 v[70:71], v[38:41], off offset:256
	s_waitcnt lgkmcnt(1)
	v_add_f32_e32 v34, v58, v34
	s_waitcnt lgkmcnt(0)
	v_add_f32_e32 v35, v59, v35
	ds_bpermute_b32 v36, v136, v34
	ds_bpermute_b32 v37, v136, v35
	s_and_saveexec_b64 s[24:25], s[40:41]
	s_cbranch_execz .LBB0_742
	s_waitcnt lgkmcnt(1)
	v_add_f32_e32 v34, v34, v36
	s_waitcnt lgkmcnt(0)
	v_add_f32_e32 v35, v35, v37
	global_atomic_add_f32 v137, v34, s[82:83] offset:1152
	global_atomic_add_f32 v137, v35, s[82:83] offset:1156
; __device__ __forceinline__ unsigned cvt_pk_bf16(float lo, float hi) { unsigned r; asm volatile("v_cvt_pk_bf16_f32 %0, %1, %2" : "=v"(r) : "v"(lo), "v"(hi)); return r; }
; __device__ __forceinline__ void stats_mr(const f32x2 s, float& mu, float& r) { mu = s.x * (1.0f / 1024.0f); const float var = s.y * (1.0f / 1024.0f) - mu * mu; r = __builtin_amdgcn_rsqf(var + 1e-5f); }
;     __device__ __forceinline__ void operator()(const f32x4 (&acc)[2][2][4][2], const Unit& u, int wr, int wc, int fr, int fq) const {
;     ...
;         for (int g = 0; g < 8; ++g) { const int ai = g >> 2, m = g & 3; const int rr = ai * HALF + m * 16, rn = ((g + 1) >> 2) * HALF + ((g + 1) & 3) * 16;
;             f32x2 sv_n = sv_c; if (g + 1 < 8) sv_n = *(const f32x2*)(sp + (size_t)rn * 8 + ls);
;             float mu, r; stats_mr(sv_c, mu, r); float s1 = 0.f, s2 = 0.f;
; #pragma unroll
;             for (int bj = 0; bj < 2; ++bj) { const size_t ro = (size_t)rr * ldc + bj * HALF;
;                 f32x4 q0 = p0, q1 = p1;
;                 if (bj == 0) { q0 = *(const f32x4*)(bp + (ro + HALF) * 4 + l4); q1 = *(const f32x4*)(bp + (ro + HALF) * 4 + l4 + 16); }
;                 else if (g + 1 < 8) { q0 = *(const f32x4*)(bp + (size_t)rn * ldc * 4 + l4); q1 = *(const f32x4*)(bp + (size_t)rn * ldc * 4 + l4 + 16); }
;                 const f32x4 z0 = gv[bj][0] * ((p0 - mu) * r) + acc[ai][bj][m][0] + cv[bj][0], z1 = gv[bj][1] * ((p1 - mu) * r) + acc[ai][bj][m][1] + cv[bj][1];
;                 *(f32x4*)(op + ro * 4 + l4) = z0; *(f32x4*)(op + ro * 4 + l4 + 16) = z1;
;                 s1 += ((z0[0] + z0[1]) + (z0[2] + z0[3])) + ((z1[0] + z1[1]) + (z1[2] + z1[3]));
;                 s2 += ((z0[0] * z0[0] + z0[1] * z0[1]) + (z0[2] * z0[2] + z0[3] * z0[3])) + ((z1[0] * z1[0] + z1[1] * z1[1]) + (z1[2] * z1[2] + z1[3] * z1[3]));
;                 if (zb) { u32x4 w; w.x = cvt_pk_bf16(z0[0], z0[1]); w.y = cvt_pk_bf16(z0[2], z0[3]); w.z = cvt_pk_bf16(z1[0], z1[1]); w.w = cvt_pk_bf16(z1[2], z1[3]); *(u32x4*)(zp + ro * 2 + l2) = w; }
;                 p0 = q0; p1 = q1; }
;             s1 += __shfl_xor(s1, 16); s2 += __shfl_xor(s2, 16); s1 += __shfl_xor(s1, 32); s2 += __shfl_xor(s2, 32);
;             if (fq == 0) { atomicAdd(osp + 2 * (rr + fr), s1); atomicAdd(osp + 2 * (rr + fr) + 1, s2); }
;             sv_c = sv_n; }
.LBB0_742:
	s_or_b64 exec, exec, s[24:25]
	s_waitcnt vmcnt(12)
	v_pk_mul_f32 v[62:63], v[74:75], s[54:55] op_sel_hi:[1,0]
	s_mov_b64 s[4:5], 0xa0200
	v_fma_f32 v34, -v62, v62, v63
	v_add_f32_e32 v34, 0x3727c5ac, v34
	v_rsq_f32_e32 v60, v34
	v_lshl_add_u64 v[34:35], v[202:203], 0, s[4:5]
	global_load_dwordx2 v[58:59], v[204:205], off offset:1408
	s_waitcnt lgkmcnt(0)
	v_add_co_u32_e32 v34, vcc, 0xb0000, v202
	v_addc_co_u32_e32 v35, vcc, 0, v203, vcc
	global_load_dwordx4 v[38:41], v[34:35], off
	s_nop 0
	global_load_dwordx4 v[34:37], v[34:35], off offset:16
	s_waitcnt vmcnt(14)
	v_sub_f32_e32 v55, v55, v62
	v_sub_f32_e32 v54, v54, v62
	v_sub_f32_e32 v57, v57, v62
	v_sub_f32_e32 v56, v56, v62
	v_pk_mul_f32 v[56:57], v[60:61], v[56:57] op_sel_hi:[0,1]
	v_pk_mul_f32 v[54:55], v[60:61], v[54:55] op_sel_hi:[0,1]
	s_waitcnt vmcnt(13)
	v_sub_f32_e32 v51, v51, v62
	v_sub_f32_e32 v50, v50, v62
	v_sub_f32_e32 v53, v53, v62
	v_sub_f32_e32 v52, v52, v62
	v_pk_fma_f32 v[30:31], v[170:171], v[54:55], v[30:31]
	v_pk_fma_f32 v[32:33], v[162:163], v[56:57], v[32:33]
	v_pk_mul_f32 v[52:53], v[60:61], v[52:53] op_sel_hi:[0,1]
	v_pk_mul_f32 v[50:51], v[60:61], v[50:51] op_sel_hi:[0,1]
	v_pk_add_f32 v[32:33], v[186:187], v[32:33]
	v_pk_add_f32 v[30:31], v[188:189], v[30:31]
	v_pk_fma_f32 v[26:27], v[196:197], v[50:51], v[26:27]
	v_pk_fma_f32 v[28:29], v[194:195], v[52:53], v[28:29]
	v_pk_add_f32 v[26:27], v[192:193], v[26:27]
	v_pk_add_f32 v[28:29], v[190:191], v[28:29]
	v_add_f32_e32 v52, v30, v31
	v_add_f32_e32 v53, v32, v33
	v_add_f32_e32 v52, v52, v53
	v_add_f32_e32 v53, v26, v27
	v_add_f32_e32 v54, v28, v29
	v_add_f32_e32 v53, v53, v54
	v_add_f32_e32 v52, v52, v53
	v_add_f32_e32 v56, 0, v52
	v_mul_f32_e32 v52, v31, v31
	v_mul_f32_e32 v53, v33, v33
	v_fmac_f32_e32 v52, v30, v30
	v_fmac_f32_e32 v53, v32, v32
	v_add_f32_e32 v52, v52, v53
	v_mul_f32_e32 v53, v27, v27
	v_mul_f32_e32 v54, v29, v29
	v_add_co_u32_e32 v50, vcc, s1, v200
	v_fmac_f32_e32 v53, v26, v26
	v_fmac_f32_e32 v54, v28, v28
	v_addc_co_u32_e32 v51, vcc, 0, v201, vcc
	v_add_f32_e32 v53, v53, v54
	s_mov_b32 s1, 0x50000
	v_add_f32_e32 v57, v52, v53
	v_add_co_u32_e32 v52, vcc, s1, v198
	s_mov_b32 s1, 0xb0000
	s_nop 0
	v_addc_co_u32_e32 v53, vcc, 0, v199, vcc
	s_mov_b64 s[4:5], 0xb0000
	v_add_co_u32_e32 v54, vcc, s1, v202
	global_store_dwordx4 v[50:51], v[30:33], off nt
	global_store_dwordx4 v[50:51], v[26:29], off offset:16 nt
	v_addc_co_u32_e32 v55, vcc, 0, v203, vcc
	v_cvt_pk_bf16_f32 v30, v30, v31
	v_cvt_pk_bf16_f32 v31, v32, v33
	v_cvt_pk_bf16_f32 v32, v26, v27
	v_cvt_pk_bf16_f32 v33, v28, v29
	global_store_dwordx4 v[52:53], v[30:33], off
	v_lshl_add_u64 v[26:27], v[202:203], 0, s[4:5]
	s_nop 0
	v_add_co_u32_e32 v30, vcc, 0xb0200, v202
	v_addc_co_u32_e32 v31, vcc, 0, v203, vcc
	global_load_dwordx4 v[26:29], v[30:31], off
	s_nop 0
	global_load_dwordx4 v[30:33], v[30:31], off offset:16
	s_waitcnt vmcnt(14)
	v_sub_f32_e32 v47, v47, v62
	v_sub_f32_e32 v46, v46, v62
	v_sub_f32_e32 v49, v49, v62
	v_sub_f32_e32 v48, v48, v62
	v_pk_mul_f32 v[48:49], v[60:61], v[48:49] op_sel_hi:[0,1]
	v_pk_mul_f32 v[46:47], v[60:61], v[46:47] op_sel_hi:[0,1]
	s_waitcnt vmcnt(13)
	v_sub_f32_e32 v43, v43, v62
	v_sub_f32_e32 v42, v42, v62
	v_sub_f32_e32 v45, v45, v62
	v_sub_f32_e32 v44, v44, v62
	v_pk_fma_f32 v[22:23], v[164:165], v[46:47], v[22:23]
	v_pk_fma_f32 v[24:25], v[160:161], v[48:49], v[24:25]
	v_pk_mul_f32 v[44:45], v[60:61], v[44:45] op_sel_hi:[0,1]
	v_pk_mul_f32 v[42:43], v[60:61], v[42:43] op_sel_hi:[0,1]
	v_pk_add_f32 v[24:25], v[174:175], v[24:25]
	v_pk_add_f32 v[22:23], v[176:177], v[22:23]
	v_pk_fma_f32 v[18:19], v[178:179], v[42:43], v[18:19]
	v_pk_fma_f32 v[20:21], v[172:173], v[44:45], v[20:21]
	v_pk_add_f32 v[18:19], v[168:169], v[18:19]
	v_pk_add_f32 v[20:21], v[166:167], v[20:21]
	v_add_f32_e32 v42, v22, v23
	v_add_f32_e32 v43, v24, v25
	v_add_f32_e32 v42, v42, v43
	v_add_f32_e32 v43, v18, v19
	v_add_f32_e32 v44, v20, v21
	v_add_f32_e32 v43, v43, v44
	v_add_f32_e32 v42, v42, v43
	v_mul_f32_e32 v43, v23, v23
	v_mul_f32_e32 v44, v25, v25
	v_fmac_f32_e32 v43, v22, v22
	v_fmac_f32_e32 v44, v24, v24
	v_add_f32_e32 v43, v43, v44
	v_mul_f32_e32 v44, v19, v19
	v_mul_f32_e32 v45, v21, v21
	v_fmac_f32_e32 v44, v18, v18
	v_fmac_f32_e32 v45, v20, v20
	v_add_f32_e32 v44, v44, v45
	v_add_f32_e32 v43, v43, v44
	v_add_f32_e32 v42, v56, v42
	v_add_f32_e32 v43, v57, v43
	global_store_dwordx4 v[50:51], v[22:25], off offset:512 nt
	global_store_dwordx4 v[50:51], v[18:21], off offset:528 nt
	s_nop 0
	v_cvt_pk_bf16_f32 v22, v22, v23
	v_cvt_pk_bf16_f32 v23, v24, v25
	v_cvt_pk_bf16_f32 v24, v18, v19
	ds_bpermute_b32 v18, v133, v42
	ds_bpermute_b32 v19, v133, v43
	v_cvt_pk_bf16_f32 v25, v20, v21
	global_store_dwordx4 v[52:53], v[22:25], off offset:256
	s_waitcnt lgkmcnt(1)
	v_add_f32_e32 v18, v42, v18
	s_waitcnt lgkmcnt(0)
	v_add_f32_e32 v19, v43, v19
	ds_bpermute_b32 v20, v136, v18
	ds_bpermute_b32 v21, v136, v19
	s_and_saveexec_b64 s[24:25], s[40:41]
	s_cbranch_execz .LBB0_744
	s_waitcnt lgkmcnt(1)
	v_add_f32_e32 v18, v18, v20
	s_waitcnt lgkmcnt(0)
	v_add_f32_e32 v19, v19, v21
	global_atomic_add_f32 v137, v18, s[82:83] offset:1280
	global_atomic_add_f32 v137, v19, s[82:83] offset:1284
; __device__ __forceinline__ unsigned cvt_pk_bf16(float lo, float hi) { unsigned r; asm volatile("v_cvt_pk_bf16_f32 %0, %1, %2" : "=v"(r) : "v"(lo), "v"(hi)); return r; }
; __device__ __forceinline__ void stats_mr(const f32x2 s, float& mu, float& r) { mu = s.x * (1.0f / 1024.0f); const float var = s.y * (1.0f / 1024.0f) - mu * mu; r = __builtin_amdgcn_rsqf(var + 1e-5f); }
;     __device__ __forceinline__ void operator()(const f32x4 (&acc)[2][2][4][2], const Unit& u, int wr, int wc, int fr, int fq) const {
;     ...
;         for (int g = 0; g < 8; ++g) { const int ai = g >> 2, m = g & 3; const int rr = ai * HALF + m * 16, rn = ((g + 1) >> 2) * HALF + ((g + 1) & 3) * 16;
;             f32x2 sv_n = sv_c; if (g + 1 < 8) sv_n = *(const f32x2*)(sp + (size_t)rn * 8 + ls);
;             float mu, r; stats_mr(sv_c, mu, r); float s1 = 0.f, s2 = 0.f;
; #pragma unroll
;             for (int bj = 0; bj < 2; ++bj) { const size_t ro = (size_t)rr * ldc + bj * HALF;
;                 f32x4 q0 = p0, q1 = p1;
;                 if (bj == 0) { q0 = *(const f32x4*)(bp + (ro + HALF) * 4 + l4); q1 = *(const f32x4*)(bp + (ro + HALF) * 4 + l4 + 16); }
;                 else if (g + 1 < 8) { q0 = *(const f32x4*)(bp + (size_t)rn * ldc * 4 + l4); q1 = *(const f32x4*)(bp + (size_t)rn * ldc * 4 + l4 + 16); }
;                 const f32x4 z0 = gv[bj][0] * ((p0 - mu) * r) + acc[ai][bj][m][0] + cv[bj][0], z1 = gv[bj][1] * ((p1 - mu) * r) + acc[ai][bj][m][1] + cv[bj][1];
;                 *(f32x4*)(op + ro * 4 + l4) = z0; *(f32x4*)(op + ro * 4 + l4 + 16) = z1;
;                 s1 += ((z0[0] + z0[1]) + (z0[2] + z0[3])) + ((z1[0] + z1[1]) + (z1[2] + z1[3]));
;                 s2 += ((z0[0] * z0[0] + z0[1] * z0[1]) + (z0[2] * z0[2] + z0[3] * z0[3])) + ((z1[0] * z1[0] + z1[1] * z1[1]) + (z1[2] * z1[2] + z1[3] * z1[3]));
;                 if (zb) { u32x4 w; w.x = cvt_pk_bf16(z0[0], z0[1]); w.y = cvt_pk_bf16(z0[2], z0[3]); w.z = cvt_pk_bf16(z1[0], z1[1]); w.w = cvt_pk_bf16(z1[2], z1[3]); *(u32x4*)(zp + ro * 2 + l2) = w; }
;                 p0 = q0; p1 = q1; }
;             s1 += __shfl_xor(s1, 16); s2 += __shfl_xor(s2, 16); s1 += __shfl_xor(s1, 32); s2 += __shfl_xor(s2, 32);
;             if (fq == 0) { atomicAdd(osp + 2 * (rr + fr), s1); atomicAdd(osp + 2 * (rr + fr) + 1, s2); }
;             sv_c = sv_n; }
.LBB0_744:
	s_or_b64 exec, exec, s[24:25]
	s_mov_b64 s[4:5], 0xb0200
	s_waitcnt lgkmcnt(0)
	v_lshl_add_u64 v[22:23], v[202:203], 0, s[4:5]
	s_waitcnt vmcnt(12)
	v_pk_mul_f32 v[42:43], v[58:59], s[54:55] op_sel_hi:[1,0]
	v_add_co_u32_e32 v44, vcc, s1, v200
	v_fma_f32 v43, -v42, v42, v43
	v_add_f32_e32 v43, 0x3727c5ac, v43
	v_rsq_f32_e32 v48, v43
	s_waitcnt vmcnt(11)
	v_sub_f32_e32 v39, v39, v42
	v_sub_f32_e32 v38, v38, v42
	v_sub_f32_e32 v41, v41, v42
	v_sub_f32_e32 v40, v40, v42
	s_waitcnt vmcnt(10)
	v_sub_f32_e32 v35, v35, v42
	v_sub_f32_e32 v34, v34, v42
	v_sub_f32_e32 v37, v37, v42
	v_sub_f32_e32 v36, v36, v42
	v_pk_mul_f32 v[40:41], v[48:49], v[40:41] op_sel_hi:[0,1]
	v_pk_mul_f32 v[38:39], v[48:49], v[38:39] op_sel_hi:[0,1]
	v_pk_mul_f32 v[36:37], v[48:49], v[36:37] op_sel_hi:[0,1]
	v_pk_mul_f32 v[34:35], v[48:49], v[34:35] op_sel_hi:[0,1]
	v_pk_fma_f32 v[14:15], v[170:171], v[38:39], v[14:15]
	v_pk_fma_f32 v[16:17], v[162:163], v[40:41], v[16:17]
	v_pk_fma_f32 v[34:35], v[196:197], v[34:35], v[10:11]
	v_pk_fma_f32 v[36:37], v[194:195], v[36:37], v[12:13]
	v_pk_add_f32 v[12:13], v[186:187], v[16:17]
	v_pk_add_f32 v[10:11], v[188:189], v[14:15]
	v_pk_add_f32 v[16:17], v[190:191], v[36:37]
	v_pk_add_f32 v[14:15], v[192:193], v[34:35]
	v_addc_co_u32_e32 v45, vcc, 0, v201, vcc
	s_mov_b32 s1, 0x58000
	v_add_f32_e32 v38, v10, v11
	v_add_f32_e32 v39, v12, v13
	v_add_f32_e32 v40, v14, v15
	v_add_f32_e32 v41, v16, v17
	v_mul_f32_e32 v43, v11, v11
	v_mul_f32_e32 v49, v13, v13
	v_mul_f32_e32 v50, v15, v15
	v_mul_f32_e32 v51, v17, v17
	v_add_co_u32_e32 v46, vcc, s1, v198
	global_store_dwordx4 v[44:45], v[10:13], off nt
	global_store_dwordx4 v[44:45], v[14:17], off offset:16 nt
	v_cvt_pk_bf16_f32 v34, v10, v11
	v_cvt_pk_bf16_f32 v35, v12, v13
	v_fmac_f32_e32 v43, v10, v10
	v_add_f32_e32 v11, v38, v39
	v_add_f32_e32 v13, v40, v41
	v_fmac_f32_e32 v49, v12, v12
	v_fmac_f32_e32 v50, v14, v14
	v_fmac_f32_e32 v51, v16, v16
	v_addc_co_u32_e32 v47, vcc, 0, v199, vcc
	v_add_f32_e32 v10, v11, v13
	v_add_f32_e32 v11, v43, v49
	v_add_f32_e32 v12, v50, v51
	v_cvt_pk_bf16_f32 v36, v14, v15
	v_cvt_pk_bf16_f32 v37, v16, v17
	global_store_dwordx4 v[46:47], v[34:37], off
	s_waitcnt vmcnt(9)
	v_sub_f32_e32 v13, v29, v42
	v_add_f32_e32 v34, 0, v10
	v_add_f32_e32 v35, v11, v12
	v_sub_f32_e32 v11, v27, v42
	v_sub_f32_e32 v10, v26, v42
	v_sub_f32_e32 v12, v28, v42
	v_pk_mul_f32 v[12:13], v[48:49], v[12:13] op_sel_hi:[0,1]
	v_pk_mul_f32 v[10:11], v[48:49], v[10:11] op_sel_hi:[0,1]
	s_waitcnt vmcnt(8)
	v_sub_f32_e32 v15, v31, v42
	v_sub_f32_e32 v14, v30, v42
	v_sub_f32_e32 v17, v33, v42
	v_sub_f32_e32 v16, v32, v42
	v_pk_fma_f32 v[6:7], v[164:165], v[10:11], v[6:7]
	v_pk_fma_f32 v[8:9], v[160:161], v[12:13], v[8:9]
	v_pk_mul_f32 v[10:11], v[48:49], v[16:17] op_sel_hi:[0,1]
	v_pk_mul_f32 v[12:13], v[48:49], v[14:15] op_sel_hi:[0,1]
	v_pk_add_f32 v[8:9], v[174:175], v[8:9]
	v_pk_add_f32 v[6:7], v[176:177], v[6:7]
	v_pk_fma_f32 v[2:3], v[178:179], v[12:13], v[2:3]
	v_pk_fma_f32 v[4:5], v[172:173], v[10:11], v[4:5]
	v_pk_add_f32 v[10:11], v[168:169], v[2:3]
	v_pk_add_f32 v[12:13], v[166:167], v[4:5]
	v_add_f32_e32 v2, v6, v7
	v_add_f32_e32 v3, v8, v9
	v_add_f32_e32 v2, v2, v3
	v_add_f32_e32 v3, v10, v11
	v_add_f32_e32 v4, v12, v13
	v_add_f32_e32 v3, v3, v4
	v_add_f32_e32 v2, v2, v3
	v_mul_f32_e32 v3, v7, v7
	v_mul_f32_e32 v4, v9, v9
	v_fmac_f32_e32 v3, v6, v6
	v_fmac_f32_e32 v4, v8, v8
	v_add_f32_e32 v3, v3, v4
	v_mul_f32_e32 v4, v11, v11
	v_mul_f32_e32 v5, v13, v13
	v_fmac_f32_e32 v4, v10, v10
	v_fmac_f32_e32 v5, v12, v12
	v_add_f32_e32 v4, v4, v5
	v_add_f32_e32 v3, v3, v4
	v_add_f32_e32 v2, v34, v2
	v_add_f32_e32 v3, v35, v3
	ds_bpermute_b32 v4, v133, v2
	ds_bpermute_b32 v5, v133, v3
	global_store_dwordx4 v[44:45], v[6:9], off offset:512 nt
	global_store_dwordx4 v[44:45], v[10:13], off offset:528 nt
	s_waitcnt lgkmcnt(1)
	v_add_f32_e32 v2, v2, v4
	s_waitcnt lgkmcnt(0)
	v_add_f32_e32 v3, v3, v5
	ds_bpermute_b32 v4, v136, v2
	ds_bpermute_b32 v5, v136, v3
	v_cvt_pk_bf16_f32 v6, v6, v7
	v_cvt_pk_bf16_f32 v7, v8, v9
	v_cvt_pk_bf16_f32 v8, v10, v11
	v_cvt_pk_bf16_f32 v9, v12, v13
	global_store_dwordx4 v[46:47], v[6:9], off offset:256
	s_and_saveexec_b64 s[24:25], s[40:41]
	s_cbranch_execz .LBB0_746
	s_waitcnt lgkmcnt(1)
	v_add_f32_e32 v2, v2, v4
	s_waitcnt lgkmcnt(0)
	v_add_f32_e32 v3, v3, v5
	global_atomic_add_f32 v137, v2, s[82:83] offset:1408
	global_atomic_add_f32 v137, v3, s[82:83] offset:1412
